# v85 + P2 phase code moved by 16 bytes (240-byte compensation at the next phase entry); pad sizes chosen by repeat-amplified timing scans
# baseline (speedup 1.0000x reference)
.LBB0_559:
	s_nop 0
	s_nop 0
	s_nop 0
	s_nop 0
	s_cmp_lt_i32 s84, 3
	s_cselect_b64 s[0:1], -1, 0
	s_cmp_gt_i32 s85, 2
	s_cselect_b64 s[2:3], -1, 0
	s_and_b64 s[0:1], s[0:1], s[2:3]
	s_andn2_b64 vcc, exec, s[0:1]
	s_cbranch_vccnz .LBB0_803
	v_and_b32_e32 v148, 15, v170
	v_bfe_u32 v1, v170, 4, 2
	s_cmpk_gt_i32 s86, 0xc5f
	v_readfirstlane_b32 s33, v170
	s_barrier
	s_cbranch_scc1 .LBB0_572
	s_waitcnt vmcnt(15)
	v_lshrrev_b32_e32 v2, 5, v170
	v_lshrrev_b32_e32 v4, 1, v170
	v_and_b32_e32 v2, 4, v2
	v_bfe_u32 v3, v170, 2, 2
	v_and_b32_e32 v4, 24, v4
	v_or3_b32 v2, v2, v3, v4
	v_lshlrev_b32_e32 v3, 4, v170
	s_waitcnt vmcnt(13)
	v_add_u32_e32 v10, 0x2000, v3
	v_lshrrev_b32_e32 v4, 7, v10
	s_movk_i32 s0, 0xe0
	v_and_b32_e32 v6, 32, v170
	s_add_u32 s40, s30, 0xe100000
	v_and_or_b32 v5, v4, s0, v2
	v_bitop3_b32 v11, v3, v6, 48 bitop3:0x6c
	v_and_b32_e32 v12, 64, v170
	v_bfe_u32 v13, v170, 2, 4
	s_movk_i32 s0, 0xf0
	s_addc_u32 s41, s31, 0
	v_or_b32_e32 v3, v11, v12
	v_and_or_b32 v4, v4, s0, v13
	s_add_u32 s48, s30, 0x12900000
	v_lshl_or_b32 v132, v4, 11, v3
	v_lshrrev_b32_e32 v4, 3, v170
	s_movk_i32 s0, 0x60
	s_addc_u32 s49, s31, 0
	v_and_or_b32 v2, v4, s0, v2
	s_movk_i32 s0, 0x70
	s_ashr_i32 s50, s86, 31
	v_lshl_or_b32 v134, v2, 11, v3
	v_and_or_b32 v2, v4, s0, v13
	s_lshr_b32 s0, s50, 29
	s_add_i32 s0, s86, s0
	s_ashr_i32 s1, s0, 3
	s_and_b32 s0, s0, -8
	s_sub_i32 s0, s86, s0
	s_cmp_lt_i32 s0, 0
	s_movk_i32 s51, 0x18d
	s_cselect_b32 s2, s51, 0x18c
	s_mul_i32 s0, s2, s0
	s_add_i32 s0, s0, s1
	s_mul_hi_i32 s1, s0, 0x2e8ba2e9
	s_lshr_b32 s2, s1, 31
	s_ashr_i32 s1, s1, 5
	s_add_i32 s1, s1, s2
	s_lshl_b32 s3, s1, 3
	s_mulk_i32 s1, 0xb0
	s_sub_i32 s0, s0, s1
	s_bfe_u32 s1, s0, 0x3001c
	s_add_i32 s1, s0, s1
	s_sext_i32_i16 s2, s1
	s_and_b32 s1, s1, 0xfff8
	s_sub_i32 s0, s0, s1
	s_sext_i32_i16 s0, s0
	s_lshr_b32 s2, s2, 3
	s_add_i32 s14, s3, s0
	s_ashr_i32 s15, s14, 31
	s_bfe_i64 s[4:5], s[2:3], 0x100000
	s_lshl_b64 s[0:1], s[14:15], 19
	s_lshl_b64 s[4:5], s[4:5], 19
	s_add_u32 s34, s48, s4
	s_addc_u32 s35, s49, s5
	s_add_u32 s16, s40, s0
	s_addc_u32 s17, s41, s1
	s_lshr_b32 s6, s33, 6
	s_lshr_b32 s3, s33, 8
	s_lshl_b32 s52, s6, 10
	s_add_u32 s0, s16, 0x40000
	s_addc_u32 s1, s17, 0
	s_add_u32 s4, s34, 0x40000
	s_addc_u32 s5, s35, 0
	s_add_i32 s53, s52, 0
	s_add_i32 m0, s53, 0x10000
	v_lshl_or_b32 v130, v5, 11, v3
	global_load_lds_dwordx4 v134, s[34:35]
	s_add_i32 m0, s53, 0x12000
	v_lshl_or_b32 v136, v2, 11, v3
	global_load_lds_dwordx4 v130, s[34:35]
	s_mov_b32 m0, s53
	s_add_i32 s54, s53, 0x2000
	global_load_lds_dwordx4 v136, s[16:17]
	s_mov_b32 m0, s54
	s_add_i32 s55, s53, 0x4000
	global_load_lds_dwordx4 v132, s[16:17]
	s_add_i32 m0, s53, 0x14000
	s_add_i32 s56, s53, 0x6000
	global_load_lds_dwordx4 v134, s[4:5]
	s_add_i32 m0, s53, 0x16000
	v_mov_b32_e32 v139, 0
	global_load_lds_dwordx4 v130, s[4:5]
	s_mov_b32 m0, s55
	v_mov_b32_e32 v135, v139
	global_load_lds_dwordx4 v136, s[0:1]
	s_mov_b32 m0, s56
	v_mov_b32_e32 v131, v139
	global_load_lds_dwordx4 v132, s[0:1]
	v_mov_b32_e32 v137, v139
	v_mov_b32_e32 v133, v139
	s_mov_b32 s57, 0
	v_lshl_add_u64 v[2:3], s[34:35], 0, v[134:135]
	v_lshl_add_u64 v[4:5], s[34:35], 0, v[130:131]
	v_lshl_add_u64 v[6:7], s[16:17], 0, v[136:137]
	s_cmp_lg_u32 s3, 1
	v_lshl_add_u64 v[8:9], s[16:17], 0, v[132:133]
	s_cbranch_scc1 .LBB0_563
	s_barrier

.LBB0_803:
	s_nop 0
	s_nop 0
	s_nop 0
	s_nop 0
	s_nop 0
	s_nop 0
	s_nop 0
	s_nop 0
	s_nop 0
	s_nop 0
	s_nop 0
	s_nop 0
	s_nop 0
	s_nop 0
	s_nop 0
	s_nop 0
	s_nop 0
	s_nop 0
	s_nop 0
	s_nop 0
	s_nop 0
	s_nop 0
	s_nop 0
	s_nop 0
	s_nop 0
	s_nop 0
	s_nop 0
	s_nop 0
	s_nop 0
	s_nop 0
	s_nop 0
	s_nop 0
	s_nop 0
	s_nop 0
	s_nop 0
	s_nop 0
	s_nop 0
	s_nop 0
	s_nop 0
	s_nop 0
	s_nop 0
	s_nop 0
	s_nop 0
	s_nop 0
	s_nop 0
	s_nop 0
	s_nop 0
	s_nop 0
	s_nop 0
	s_nop 0
	s_nop 0
	s_nop 0
	s_nop 0
	s_nop 0
	s_nop 0
	s_nop 0
	s_nop 0
	s_nop 0
	s_nop 0
	s_nop 0
	s_cmp_lt_i32 s84, 4
	s_cselect_b64 s[0:1], -1, 0
	s_cmp_gt_i32 s85, 3
	s_cselect_b64 s[2:3], -1, 0
	s_and_b64 s[0:1], s[0:1], s[2:3]
	s_andn2_b64 vcc, exec, s[0:1]
	v_bfe_u32 v231, v170, 2, 4
	v_bfe_u32 v232, v170, 2, 2
	s_cbranch_vccnz .LBB0_1160
	v_lshrrev_b32_e32 v1, 1, v170
	v_and_b32_e32 v171, 24, v1
	v_lshrrev_b32_e32 v1, 5, v170
	v_and_b32_e32 v1, 4, v1
	s_waitcnt vmcnt(15)
	v_or3_b32 v4, v1, v232, v171
	v_lshrrev_b32_e32 v1, 3, v170
	s_movk_i32 s0, 0x70
	v_and_or_b32 v3, v1, s0, v231
	s_movk_i32 s0, 0x60
	v_lshlrev_b32_e32 v2, 4, v170
	v_and_or_b32 v5, v1, s0, v4
	v_mul_u32_u24_e32 v233, 0xb00, v3
	v_mul_u32_u24_e32 v3, 0xb00, v5
	v_add_u32_e32 v5, 0x2000, v2
	v_lshrrev_b32_e32 v5, 7, v5
	s_movk_i32 s0, 0xf0
	s_waitcnt vmcnt(14)
	v_and_or_b32 v6, v5, s0, v231
	s_movk_i32 s0, 0xe0
	v_and_or_b32 v4, v5, s0, v4
	s_cmpk_lt_i32 s86, 0x200
	v_mul_u32_u24_e32 v234, 0xb00, v6
	v_mul_u32_u24_e32 v4, 0xb00, v4
	v_bfe_u32 v183, v170, 4, 2
	s_cselect_b64 s[0:1], -1, 0
	s_cmpk_gt_i32 s86, 0x1ff
	v_readfirstlane_b32 s53, v170
	s_barrier
	s_cbranch_scc1 .LBB0_806
	s_ashr_i32 s2, s86, 31
	s_lshr_b32 s2, s2, 29
	s_add_i32 s2, s86, s2
	s_ashr_i32 s3, s2, 3
	s_and_b32 s2, s2, -8
	s_sub_i32 s2, s86, s2
	s_lshl_b32 s5, s2, 6
	s_mul_i32 s4, s2, 0x41
	s_cmp_lt_i32 s2, 0
	s_cselect_b32 s2, s4, s5
	s_add_i32 s2, s2, s3
	s_ashr_i32 s3, s2, 31
	s_lshr_b32 s3, s3, 27
	s_add_i32 s3, s2, s3
	s_ashr_i32 s4, s3, 5
	s_and_b32 s3, s3, 0xffe0
	s_sub_i32 s2, s2, s3
	s_bfe_i32 s3, s2, 0x80000
	s_bfe_u32 s3, s3, 0x3000c
	s_add_i32 s3, s2, s3
	s_bfe_i32 s5, s3, 0x80000
	s_and_b32 s3, s3, 0xf8
	s_sub_i32 s2, s2, s3
	s_lshl_b32 s4, s4, 3
	s_sext_i32_i16 s5, s5
	s_sext_i32_i8 s2, s2
	s_add_i32 s48, s4, s2
	s_ashr_i32 s34, s5, 3
